# P0 modulation GEMV: silu table loads and the 64 weight loads per lane all in flight before first use (were 10 and 8 serial round trips)
# speedup vs baseline: 1.0127x; 1.0040x over previous
; __device__ __forceinline__ float siluf_(float v) { return v * __builtin_amdgcn_rcpf(1.0f + __builtin_amdgcn_exp2f(-LOG2E * v)); }
; __device__ __forceinline__ void mk_p0(const Ptrs& P, LAS unsigned char* lds, int tid, int wave, int lane, int bx, int G) {
;     ...
;         for (int i = tid; i < 5 * DM; i += NTHR) { const int r = i >> 10, k = i & 1023; sl[i] = siluf_(r < 4 ? P.c[(size_t)r * DM + k] : P.c_ctx[k]); }
;         __syncthreads();
;         const int col = lane & 31, half = lane >> 5; float acc[5] = {0.f, 0.f, 0.f, 0.f, 0.f};
;         const float* wp = P.mod_w + (size_t)(128 * wave + half) * NMOD + 32 * cgp + col;
; #pragma unroll 8
;         for (int i = 0; i < 64; ++i) { const float wv = __builtin_nontemporal_load(wp + (size_t)(2 * i) * NMOD); const int k = 128 * wave + 2 * i + half;
; #pragma unroll
;             for (int r = 0; r < 5; ++r) acc[r] += sl[r * DM + k] * wv; }
.LBB9_75:
	v_add_u32_e32 v89, 0x1000, v16
	v_add_u32_e32 v90, 0x2000, v16
	v_add_u32_e32 v91, 0x3000, v16
	global_load_dword v92, v16, s[46:47]
	global_load_dword v93, v16, s[46:47] offset:2048
	global_load_dword v94, v89, s[46:47]
	global_load_dword v95, v89, s[46:47] offset:2048
	global_load_dword v96, v90, s[46:47]
	global_load_dword v97, v90, s[46:47] offset:2048
	global_load_dword v98, v91, s[46:47]
	global_load_dword v99, v91, s[46:47] offset:2048
	global_load_dword v100, v16, s[50:51]
	global_load_dword v101, v16, s[50:51] offset:2048
	s_waitcnt vmcnt(9)
	v_mul_f32_e32 v102, 0xbfb8aa3b, v92
	v_exp_f32_e32 v102, v102
	s_nop 0
	v_add_f32_e32 v102, 1.0, v102
	v_rcp_f32_e32 v102, v102
	s_nop 0
	v_mul_f32_e32 v92, v92, v102
	ds_write_b32 v16, v92
	s_waitcnt vmcnt(8)
	v_mul_f32_e32 v102, 0xbfb8aa3b, v93
	v_exp_f32_e32 v102, v102
	s_nop 0
	v_add_f32_e32 v102, 1.0, v102
	v_rcp_f32_e32 v102, v102
	s_nop 0
	v_mul_f32_e32 v93, v93, v102
	ds_write_b32 v16, v93 offset:2048
	s_waitcnt vmcnt(7)
	v_mul_f32_e32 v102, 0xbfb8aa3b, v94
	v_exp_f32_e32 v102, v102
	s_nop 0
	v_add_f32_e32 v102, 1.0, v102
	v_rcp_f32_e32 v102, v102
	s_nop 0
	v_mul_f32_e32 v94, v94, v102
	ds_write_b32 v16, v94 offset:4096
	s_waitcnt vmcnt(6)
	v_mul_f32_e32 v102, 0xbfb8aa3b, v95
	v_exp_f32_e32 v102, v102
	s_nop 0
	v_add_f32_e32 v102, 1.0, v102
	v_rcp_f32_e32 v102, v102
	s_nop 0
	v_mul_f32_e32 v95, v95, v102
	ds_write_b32 v16, v95 offset:6144
	s_waitcnt vmcnt(5)
	v_mul_f32_e32 v102, 0xbfb8aa3b, v96
	v_exp_f32_e32 v102, v102
	s_nop 0
	v_add_f32_e32 v102, 1.0, v102
	v_rcp_f32_e32 v102, v102
	s_nop 0
	v_mul_f32_e32 v96, v96, v102
	ds_write_b32 v16, v96 offset:8192
	s_waitcnt vmcnt(4)
	v_mul_f32_e32 v102, 0xbfb8aa3b, v97
	v_exp_f32_e32 v102, v102
	s_nop 0
	v_add_f32_e32 v102, 1.0, v102
	v_rcp_f32_e32 v102, v102
	s_nop 0
	v_mul_f32_e32 v97, v97, v102
	ds_write_b32 v16, v97 offset:10240
	s_waitcnt vmcnt(3)
	v_mul_f32_e32 v102, 0xbfb8aa3b, v98
	v_exp_f32_e32 v102, v102
	s_nop 0
	v_add_f32_e32 v102, 1.0, v102
	v_rcp_f32_e32 v102, v102
	s_nop 0
	v_mul_f32_e32 v98, v98, v102
	ds_write_b32 v16, v98 offset:12288
	s_waitcnt vmcnt(2)
	v_mul_f32_e32 v102, 0xbfb8aa3b, v99
	v_exp_f32_e32 v102, v102
	s_nop 0
	v_add_f32_e32 v102, 1.0, v102
	v_rcp_f32_e32 v102, v102
	s_nop 0
	v_mul_f32_e32 v99, v99, v102
	ds_write_b32 v16, v99 offset:14336
	s_waitcnt vmcnt(1)
	v_mul_f32_e32 v102, 0xbfb8aa3b, v100
	v_exp_f32_e32 v102, v102
	s_nop 0
	v_add_f32_e32 v102, 1.0, v102
	v_rcp_f32_e32 v102, v102
	s_nop 0
	v_mul_f32_e32 v100, v100, v102
	ds_write_b32 v16, v100 offset:16384
	s_waitcnt vmcnt(0)
	v_mul_f32_e32 v102, 0xbfb8aa3b, v101
	v_exp_f32_e32 v102, v102
	s_nop 0
	v_add_f32_e32 v102, 1.0, v102
	v_rcp_f32_e32 v102, v102
	s_nop 0
	v_mul_f32_e32 v101, v101, v102
	ds_write_b32 v16, v101 offset:18432
	s_ashr_i32 s9, s8, 31
	v_mov_b32_e32 v10, 0
	v_lshl_add_u64 v[8:9], s[8:9], 2, v[6:7]
	s_mov_b64 s[12:13], 0
	v_mov_b32_e32 v0, v15
	v_mov_b32_e32 v11, v10
	v_mov_b32_e32 v12, v10
	v_mov_b32_e32 v13, v10
	v_mov_b32_e32 v19, v10
	s_waitcnt lgkmcnt(0)
	s_barrier
.LBB9_77:
	s_mov_b64 s[98:99], 0xc000
	v_mov_b64_e32 v[218:219], v[8:9]
	global_load_dword v88, v[218:219], off nt
	v_lshl_add_u64 v[218:219], v[218:219], 0, s[98:99]
	global_load_dword v90, v[218:219], off nt
	v_lshl_add_u64 v[218:219], v[218:219], 0, s[98:99]
	global_load_dword v92, v[218:219], off nt
	v_lshl_add_u64 v[218:219], v[218:219], 0, s[98:99]
	global_load_dword v94, v[218:219], off nt
	v_lshl_add_u64 v[218:219], v[218:219], 0, s[98:99]
	global_load_dword v96, v[218:219], off nt
	v_lshl_add_u64 v[218:219], v[218:219], 0, s[98:99]
	global_load_dword v98, v[218:219], off nt
	v_lshl_add_u64 v[218:219], v[218:219], 0, s[98:99]
	global_load_dword v100, v[218:219], off nt
	v_lshl_add_u64 v[218:219], v[218:219], 0, s[98:99]
	global_load_dword v102, v[218:219], off nt
	v_lshl_add_u64 v[218:219], v[218:219], 0, s[98:99]
	global_load_dword v104, v[218:219], off nt
	v_lshl_add_u64 v[218:219], v[218:219], 0, s[98:99]
	global_load_dword v106, v[218:219], off nt
	v_lshl_add_u64 v[218:219], v[218:219], 0, s[98:99]
	global_load_dword v108, v[218:219], off nt
	v_lshl_add_u64 v[218:219], v[218:219], 0, s[98:99]
	global_load_dword v110, v[218:219], off nt
	v_lshl_add_u64 v[218:219], v[218:219], 0, s[98:99]
	global_load_dword v112, v[218:219], off nt
	v_lshl_add_u64 v[218:219], v[218:219], 0, s[98:99]
	global_load_dword v114, v[218:219], off nt
	v_lshl_add_u64 v[218:219], v[218:219], 0, s[98:99]
	global_load_dword v116, v[218:219], off nt
	v_lshl_add_u64 v[218:219], v[218:219], 0, s[98:99]
	global_load_dword v118, v[218:219], off nt
	v_lshl_add_u64 v[218:219], v[218:219], 0, s[98:99]
	global_load_dword v120, v[218:219], off nt
	v_lshl_add_u64 v[218:219], v[218:219], 0, s[98:99]
	global_load_dword v122, v[218:219], off nt
	v_lshl_add_u64 v[218:219], v[218:219], 0, s[98:99]
	global_load_dword v124, v[218:219], off nt
	v_lshl_add_u64 v[218:219], v[218:219], 0, s[98:99]
	global_load_dword v126, v[218:219], off nt
	v_lshl_add_u64 v[218:219], v[218:219], 0, s[98:99]
	global_load_dword v128, v[218:219], off nt
	v_lshl_add_u64 v[218:219], v[218:219], 0, s[98:99]
	global_load_dword v130, v[218:219], off nt
	v_lshl_add_u64 v[218:219], v[218:219], 0, s[98:99]
	global_load_dword v132, v[218:219], off nt
	v_lshl_add_u64 v[218:219], v[218:219], 0, s[98:99]
	global_load_dword v134, v[218:219], off nt
	v_lshl_add_u64 v[218:219], v[218:219], 0, s[98:99]
	global_load_dword v136, v[218:219], off nt
	v_lshl_add_u64 v[218:219], v[218:219], 0, s[98:99]
	global_load_dword v138, v[218:219], off nt
	v_lshl_add_u64 v[218:219], v[218:219], 0, s[98:99]
	global_load_dword v140, v[218:219], off nt
; __device__ __forceinline__ void mk_p0(const Ptrs& P, LAS unsigned char* lds, int tid, int wave, int lane, int bx, int G) {
;     ...
; #pragma unroll 8
;         for (int i = 0; i < 64; ++i) { const float wv = __builtin_nontemporal_load(wp + (size_t)(2 * i) * NMOD); const int k = 128 * wave + 2 * i + half;
; #pragma unroll
;             for (int r = 0; r < 5; ++r) acc[r] += sl[r * DM + k] * wv; }
	v_lshl_add_u64 v[218:219], v[218:219], 0, s[98:99]
	global_load_dword v142, v[218:219], off nt
	v_lshl_add_u64 v[218:219], v[218:219], 0, s[98:99]
	global_load_dword v144, v[218:219], off nt
	v_lshl_add_u64 v[218:219], v[218:219], 0, s[98:99]
	global_load_dword v146, v[218:219], off nt
	v_lshl_add_u64 v[218:219], v[218:219], 0, s[98:99]
	global_load_dword v148, v[218:219], off nt
	v_lshl_add_u64 v[218:219], v[218:219], 0, s[98:99]
	global_load_dword v150, v[218:219], off nt
	v_lshl_add_u64 v[218:219], v[218:219], 0, s[98:99]
	global_load_dword v152, v[218:219], off nt
	v_lshl_add_u64 v[218:219], v[218:219], 0, s[98:99]
	global_load_dword v154, v[218:219], off nt
	v_lshl_add_u64 v[218:219], v[218:219], 0, s[98:99]
	global_load_dword v156, v[218:219], off nt
	v_lshl_add_u64 v[218:219], v[218:219], 0, s[98:99]
	global_load_dword v158, v[218:219], off nt
	v_lshl_add_u64 v[218:219], v[218:219], 0, s[98:99]
	global_load_dword v160, v[218:219], off nt
	v_lshl_add_u64 v[218:219], v[218:219], 0, s[98:99]
	global_load_dword v162, v[218:219], off nt
	v_lshl_add_u64 v[218:219], v[218:219], 0, s[98:99]
	global_load_dword v164, v[218:219], off nt
	v_lshl_add_u64 v[218:219], v[218:219], 0, s[98:99]
	global_load_dword v166, v[218:219], off nt
	v_lshl_add_u64 v[218:219], v[218:219], 0, s[98:99]
	global_load_dword v168, v[218:219], off nt
	v_lshl_add_u64 v[218:219], v[218:219], 0, s[98:99]
	global_load_dword v172, v[218:219], off nt
	v_lshl_add_u64 v[218:219], v[218:219], 0, s[98:99]
	global_load_dword v174, v[218:219], off nt
	v_lshl_add_u64 v[218:219], v[218:219], 0, s[98:99]
	global_load_dword v176, v[218:219], off nt
	v_lshl_add_u64 v[218:219], v[218:219], 0, s[98:99]
	global_load_dword v178, v[218:219], off nt
	v_lshl_add_u64 v[218:219], v[218:219], 0, s[98:99]
	global_load_dword v180, v[218:219], off nt
	v_lshl_add_u64 v[218:219], v[218:219], 0, s[98:99]
	global_load_dword v182, v[218:219], off nt
	v_lshl_add_u64 v[218:219], v[218:219], 0, s[98:99]
	global_load_dword v184, v[218:219], off nt
	v_lshl_add_u64 v[218:219], v[218:219], 0, s[98:99]
	global_load_dword v186, v[218:219], off nt
	v_lshl_add_u64 v[218:219], v[218:219], 0, s[98:99]
	global_load_dword v188, v[218:219], off nt
	v_lshl_add_u64 v[218:219], v[218:219], 0, s[98:99]
	global_load_dword v190, v[218:219], off nt
	v_lshl_add_u64 v[218:219], v[218:219], 0, s[98:99]
	global_load_dword v192, v[218:219], off nt
	v_lshl_add_u64 v[218:219], v[218:219], 0, s[98:99]
	global_load_dword v194, v[218:219], off nt
	v_lshl_add_u64 v[218:219], v[218:219], 0, s[98:99]
	global_load_dword v196, v[218:219], off nt
	v_lshl_add_u64 v[218:219], v[218:219], 0, s[98:99]
	global_load_dword v198, v[218:219], off nt
	v_lshl_add_u64 v[218:219], v[218:219], 0, s[98:99]
	global_load_dword v200, v[218:219], off nt
	v_lshl_add_u64 v[218:219], v[218:219], 0, s[98:99]
	v_add_u32_e32 v23, 0x2000, v0
	ds_read2_b32 v[36:37], v0 offset1:2
	ds_read2_b32 v[38:39], v0 offset0:4 offset1:6
	ds_read2_b32 v[40:41], v0 offset0:8 offset1:10
	ds_read2_b32 v[42:43], v0 offset0:12 offset1:14
	v_add_u32_e32 v21, 0x1000, v0
	v_add_u32_e32 v25, 0x3000, v0
	v_add_u32_e32 v27, 0x4000, v0
	ds_read2_b32 v[44:45], v21 offset1:2
	ds_read2_b32 v[46:47], v23 offset1:2
	ds_read2_b32 v[48:49], v25 offset1:2
	ds_read2_b32 v[50:51], v27 offset1:2
	ds_read2_b32 v[52:53], v21 offset0:4 offset1:6
	ds_read2_b32 v[54:55], v23 offset0:4 offset1:6
	ds_read2_b32 v[56:57], v25 offset0:4 offset1:6
	ds_read2_b32 v[58:59], v27 offset0:4 offset1:6
	ds_read2_b32 v[60:61], v21 offset0:8 offset1:10
	ds_read2_b32 v[62:63], v23 offset0:8 offset1:10
	ds_read2_b32 v[64:65], v25 offset0:8 offset1:10
	ds_read2_b32 v[66:67], v27 offset0:8 offset1:10
	ds_read2_b32 v[68:69], v21 offset0:12 offset1:14
	ds_read2_b32 v[70:71], v23 offset0:12 offset1:14
	ds_read2_b32 v[72:73], v25 offset0:12 offset1:14
	ds_read2_b32 v[74:75], v27 offset0:12 offset1:14
	s_waitcnt lgkmcnt(14)
	v_mov_b32_e32 v76, v36
	v_mov_b32_e32 v77, v44
	v_mov_b32_e32 v78, v46
	s_waitcnt lgkmcnt(13)
	v_mov_b32_e32 v79, v48
	v_mov_b32_e32 v44, v37
	v_mov_b32_e32 v48, v47
	v_mov_b32_e32 v36, v38
	s_waitcnt lgkmcnt(11)
	v_mov_b32_e32 v37, v52
	s_waitcnt lgkmcnt(10)
	v_mov_b32_e32 v46, v54
	s_waitcnt lgkmcnt(9)
	v_mov_b32_e32 v47, v56
	v_mov_b32_e32 v52, v39
	v_mov_b32_e32 v56, v55
	v_mov_b32_e32 v38, v40
	s_waitcnt lgkmcnt(7)
	v_mov_b32_e32 v39, v60
	s_waitcnt lgkmcnt(6)
	v_mov_b32_e32 v54, v62
	s_waitcnt lgkmcnt(5)
	v_mov_b32_e32 v55, v64
	v_mov_b32_e32 v60, v41
	v_mov_b32_e32 v64, v63
	v_mov_b32_e32 v40, v42
	s_waitcnt lgkmcnt(3)
	v_mov_b32_e32 v41, v68
	s_waitcnt lgkmcnt(2)
	v_mov_b32_e32 v62, v70
	s_waitcnt lgkmcnt(1)
	v_mov_b32_e32 v63, v72
	v_mov_b32_e32 v68, v43
	v_mov_b32_e32 v72, v71
	v_add_u32_e32 v0, 64, v0
	s_waitcnt vmcnt(55)
	v_pk_fma_f32 v[10:11], v[88:89], v[76:77], v[10:11] op_sel_hi:[0,1,1]
	v_pk_fma_f32 v[12:13], v[88:89], v[78:79], v[12:13] op_sel_hi:[0,1,1]
	v_fmac_f32_e32 v19, v88, v50
	s_waitcnt vmcnt(54)
	v_pk_fma_f32 v[10:11], v[90:91], v[44:45], v[10:11] op_sel_hi:[0,1,1]
	v_pk_fma_f32 v[12:13], v[90:91], v[48:49], v[12:13] op_sel_hi:[0,1,1]
	v_fmac_f32_e32 v19, v90, v51
	s_waitcnt vmcnt(53)
	v_pk_fma_f32 v[10:11], v[92:93], v[36:37], v[10:11] op_sel_hi:[0,1,1]
	v_pk_fma_f32 v[12:13], v[92:93], v[46:47], v[12:13] op_sel_hi:[0,1,1]
	v_fmac_f32_e32 v19, v92, v58
	s_waitcnt vmcnt(52)
	v_pk_fma_f32 v[10:11], v[94:95], v[52:53], v[10:11] op_sel_hi:[0,1,1]
	v_pk_fma_f32 v[12:13], v[94:95], v[56:57], v[12:13] op_sel_hi:[0,1,1]
	v_fmac_f32_e32 v19, v94, v59
	s_waitcnt vmcnt(51)
	v_pk_fma_f32 v[10:11], v[96:97], v[38:39], v[10:11] op_sel_hi:[0,1,1]
	v_pk_fma_f32 v[12:13], v[96:97], v[54:55], v[12:13] op_sel_hi:[0,1,1]
	v_fmac_f32_e32 v19, v96, v66
	s_waitcnt vmcnt(50)
; __device__ __forceinline__ void mk_p0(const Ptrs& P, LAS unsigned char* lds, int tid, int wave, int lane, int bx, int G) {
;     ...
; #pragma unroll 8
;         for (int i = 0; i < 64; ++i) { const float wv = __builtin_nontemporal_load(wp + (size_t)(2 * i) * NMOD); const int k = 128 * wave + 2 * i + half;
; #pragma unroll
;             for (int r = 0; r < 5; ++r) acc[r] += sl[r * DM + k] * wv; }
	v_pk_fma_f32 v[10:11], v[98:99], v[60:61], v[10:11] op_sel_hi:[0,1,1]
	v_pk_fma_f32 v[12:13], v[98:99], v[64:65], v[12:13] op_sel_hi:[0,1,1]
	v_fmac_f32_e32 v19, v98, v67
	s_waitcnt vmcnt(49)
	v_pk_fma_f32 v[10:11], v[100:101], v[40:41], v[10:11] op_sel_hi:[0,1,1]
	v_pk_fma_f32 v[12:13], v[100:101], v[62:63], v[12:13] op_sel_hi:[0,1,1]
	s_waitcnt lgkmcnt(0)
	v_fmac_f32_e32 v19, v100, v74
	s_waitcnt vmcnt(48)
	v_pk_fma_f32 v[10:11], v[102:103], v[68:69], v[10:11] op_sel_hi:[0,1,1]
	v_pk_fma_f32 v[12:13], v[102:103], v[72:73], v[12:13] op_sel_hi:[0,1,1]
	v_fmac_f32_e32 v19, v102, v75
	global_load_dword v202, v[218:219], off nt
	v_lshl_add_u64 v[218:219], v[218:219], 0, s[98:99]
	global_load_dword v204, v[218:219], off nt
	v_lshl_add_u64 v[218:219], v[218:219], 0, s[98:99]
	global_load_dword v206, v[218:219], off nt
	v_lshl_add_u64 v[218:219], v[218:219], 0, s[98:99]
	global_load_dword v210, v[218:219], off nt
	v_lshl_add_u64 v[218:219], v[218:219], 0, s[98:99]
	global_load_dword v212, v[218:219], off nt
	v_lshl_add_u64 v[218:219], v[218:219], 0, s[98:99]
	global_load_dword v214, v[218:219], off nt
	v_lshl_add_u64 v[218:219], v[218:219], 0, s[98:99]
	global_load_dword v216, v[218:219], off nt
	v_lshl_add_u64 v[218:219], v[218:219], 0, s[98:99]
	global_load_dword v220, v[218:219], off nt
	v_lshl_add_u64 v[218:219], v[218:219], 0, s[98:99]
	v_add_u32_e32 v23, 0x2000, v0
	ds_read2_b32 v[36:37], v0 offset1:2
	ds_read2_b32 v[38:39], v0 offset0:4 offset1:6
	ds_read2_b32 v[40:41], v0 offset0:8 offset1:10
	ds_read2_b32 v[42:43], v0 offset0:12 offset1:14
	v_add_u32_e32 v21, 0x1000, v0
	v_add_u32_e32 v25, 0x3000, v0
	v_add_u32_e32 v27, 0x4000, v0
	ds_read2_b32 v[44:45], v21 offset1:2
	ds_read2_b32 v[46:47], v23 offset1:2
	ds_read2_b32 v[48:49], v25 offset1:2
	ds_read2_b32 v[50:51], v27 offset1:2
	ds_read2_b32 v[52:53], v21 offset0:4 offset1:6
	ds_read2_b32 v[54:55], v23 offset0:4 offset1:6
	ds_read2_b32 v[56:57], v25 offset0:4 offset1:6
	ds_read2_b32 v[58:59], v27 offset0:4 offset1:6
	ds_read2_b32 v[60:61], v21 offset0:8 offset1:10
	ds_read2_b32 v[62:63], v23 offset0:8 offset1:10
	ds_read2_b32 v[64:65], v25 offset0:8 offset1:10
	ds_read2_b32 v[66:67], v27 offset0:8 offset1:10
	ds_read2_b32 v[68:69], v21 offset0:12 offset1:14
	ds_read2_b32 v[70:71], v23 offset0:12 offset1:14
	ds_read2_b32 v[72:73], v25 offset0:12 offset1:14
	ds_read2_b32 v[74:75], v27 offset0:12 offset1:14
	s_waitcnt lgkmcnt(14)
	v_mov_b32_e32 v76, v36
	v_mov_b32_e32 v77, v44
	v_mov_b32_e32 v78, v46
	s_waitcnt lgkmcnt(13)
	v_mov_b32_e32 v79, v48
	v_mov_b32_e32 v44, v37
	v_mov_b32_e32 v48, v47
	v_mov_b32_e32 v36, v38
	s_waitcnt lgkmcnt(11)
	v_mov_b32_e32 v37, v52
	s_waitcnt lgkmcnt(10)
	v_mov_b32_e32 v46, v54
	s_waitcnt lgkmcnt(9)
	v_mov_b32_e32 v47, v56
	v_mov_b32_e32 v52, v39
	v_mov_b32_e32 v56, v55
	v_mov_b32_e32 v38, v40
	s_waitcnt lgkmcnt(7)
	v_mov_b32_e32 v39, v60
	s_waitcnt lgkmcnt(6)
	v_mov_b32_e32 v54, v62
	s_waitcnt lgkmcnt(5)
	v_mov_b32_e32 v55, v64
	v_mov_b32_e32 v60, v41
	v_mov_b32_e32 v64, v63
	v_mov_b32_e32 v40, v42
	s_waitcnt lgkmcnt(3)
	v_mov_b32_e32 v41, v68
	s_waitcnt lgkmcnt(2)
	v_mov_b32_e32 v62, v70
	s_waitcnt lgkmcnt(1)
	v_mov_b32_e32 v63, v72
	v_mov_b32_e32 v68, v43
	v_mov_b32_e32 v72, v71
	v_add_u32_e32 v0, 64, v0
	s_waitcnt vmcnt(55)
	v_pk_fma_f32 v[10:11], v[104:105], v[76:77], v[10:11] op_sel_hi:[0,1,1]
	v_pk_fma_f32 v[12:13], v[104:105], v[78:79], v[12:13] op_sel_hi:[0,1,1]
	v_fmac_f32_e32 v19, v104, v50
	s_waitcnt vmcnt(54)
	v_pk_fma_f32 v[10:11], v[106:107], v[44:45], v[10:11] op_sel_hi:[0,1,1]
	v_pk_fma_f32 v[12:13], v[106:107], v[48:49], v[12:13] op_sel_hi:[0,1,1]
	v_fmac_f32_e32 v19, v106, v51
	s_waitcnt vmcnt(53)
	v_pk_fma_f32 v[10:11], v[108:109], v[36:37], v[10:11] op_sel_hi:[0,1,1]
	v_pk_fma_f32 v[12:13], v[108:109], v[46:47], v[12:13] op_sel_hi:[0,1,1]
	v_fmac_f32_e32 v19, v108, v58
	s_waitcnt vmcnt(52)
	v_pk_fma_f32 v[10:11], v[110:111], v[52:53], v[10:11] op_sel_hi:[0,1,1]
	v_pk_fma_f32 v[12:13], v[110:111], v[56:57], v[12:13] op_sel_hi:[0,1,1]
	v_fmac_f32_e32 v19, v110, v59
	s_waitcnt vmcnt(51)
	v_pk_fma_f32 v[10:11], v[112:113], v[38:39], v[10:11] op_sel_hi:[0,1,1]
	v_pk_fma_f32 v[12:13], v[112:113], v[54:55], v[12:13] op_sel_hi:[0,1,1]
	v_fmac_f32_e32 v19, v112, v66
	s_waitcnt vmcnt(50)
	v_pk_fma_f32 v[10:11], v[114:115], v[60:61], v[10:11] op_sel_hi:[0,1,1]
	v_pk_fma_f32 v[12:13], v[114:115], v[64:65], v[12:13] op_sel_hi:[0,1,1]
	v_fmac_f32_e32 v19, v114, v67
	s_waitcnt vmcnt(49)
	v_pk_fma_f32 v[10:11], v[116:117], v[40:41], v[10:11] op_sel_hi:[0,1,1]
	v_pk_fma_f32 v[12:13], v[116:117], v[62:63], v[12:13] op_sel_hi:[0,1,1]
	s_waitcnt lgkmcnt(0)
	v_fmac_f32_e32 v19, v116, v74
	s_waitcnt vmcnt(48)
	v_pk_fma_f32 v[10:11], v[118:119], v[68:69], v[10:11] op_sel_hi:[0,1,1]
	v_pk_fma_f32 v[12:13], v[118:119], v[72:73], v[12:13] op_sel_hi:[0,1,1]
	v_fmac_f32_e32 v19, v118, v75
	v_add_u32_e32 v23, 0x2000, v0
	ds_read2_b32 v[36:37], v0 offset1:2
	ds_read2_b32 v[38:39], v0 offset0:4 offset1:6
	ds_read2_b32 v[40:41], v0 offset0:8 offset1:10
	ds_read2_b32 v[42:43], v0 offset0:12 offset1:14
	v_add_u32_e32 v21, 0x1000, v0
	v_add_u32_e32 v25, 0x3000, v0
	v_add_u32_e32 v27, 0x4000, v0
	ds_read2_b32 v[44:45], v21 offset1:2
	ds_read2_b32 v[46:47], v23 offset1:2
	ds_read2_b32 v[48:49], v25 offset1:2
	ds_read2_b32 v[50:51], v27 offset1:2
	ds_read2_b32 v[52:53], v21 offset0:4 offset1:6
	ds_read2_b32 v[54:55], v23 offset0:4 offset1:6
	ds_read2_b32 v[56:57], v25 offset0:4 offset1:6
	ds_read2_b32 v[58:59], v27 offset0:4 offset1:6
	ds_read2_b32 v[60:61], v21 offset0:8 offset1:10
	ds_read2_b32 v[62:63], v23 offset0:8 offset1:10
	ds_read2_b32 v[64:65], v25 offset0:8 offset1:10
	ds_read2_b32 v[66:67], v27 offset0:8 offset1:10
	ds_read2_b32 v[68:69], v21 offset0:12 offset1:14
	ds_read2_b32 v[70:71], v23 offset0:12 offset1:14
	ds_read2_b32 v[72:73], v25 offset0:12 offset1:14
	ds_read2_b32 v[74:75], v27 offset0:12 offset1:14
	s_waitcnt lgkmcnt(14)
; __device__ __forceinline__ void mk_p0(const Ptrs& P, LAS unsigned char* lds, int tid, int wave, int lane, int bx, int G) {
;     ...
; #pragma unroll 8
;         for (int i = 0; i < 64; ++i) { const float wv = __builtin_nontemporal_load(wp + (size_t)(2 * i) * NMOD); const int k = 128 * wave + 2 * i + half;
; #pragma unroll
;             for (int r = 0; r < 5; ++r) acc[r] += sl[r * DM + k] * wv; }
	v_mov_b32_e32 v76, v36
	v_mov_b32_e32 v77, v44
	v_mov_b32_e32 v78, v46
	s_waitcnt lgkmcnt(13)
	v_mov_b32_e32 v79, v48
	v_mov_b32_e32 v44, v37
	v_mov_b32_e32 v48, v47
	v_mov_b32_e32 v36, v38
	s_waitcnt lgkmcnt(11)
	v_mov_b32_e32 v37, v52
	s_waitcnt lgkmcnt(10)
	v_mov_b32_e32 v46, v54
	s_waitcnt lgkmcnt(9)
	v_mov_b32_e32 v47, v56
	v_mov_b32_e32 v52, v39
	v_mov_b32_e32 v56, v55
	v_mov_b32_e32 v38, v40
	s_waitcnt lgkmcnt(7)
	v_mov_b32_e32 v39, v60
	s_waitcnt lgkmcnt(6)
	v_mov_b32_e32 v54, v62
	s_waitcnt lgkmcnt(5)
	v_mov_b32_e32 v55, v64
	v_mov_b32_e32 v60, v41
	v_mov_b32_e32 v64, v63
	v_mov_b32_e32 v40, v42
	s_waitcnt lgkmcnt(3)
	v_mov_b32_e32 v41, v68
	s_waitcnt lgkmcnt(2)
	v_mov_b32_e32 v62, v70
	s_waitcnt lgkmcnt(1)
	v_mov_b32_e32 v63, v72
	v_mov_b32_e32 v68, v43
	v_mov_b32_e32 v72, v71
	v_add_u32_e32 v0, 64, v0
	s_waitcnt vmcnt(47)
	v_pk_fma_f32 v[10:11], v[120:121], v[76:77], v[10:11] op_sel_hi:[0,1,1]
	v_pk_fma_f32 v[12:13], v[120:121], v[78:79], v[12:13] op_sel_hi:[0,1,1]
	v_fmac_f32_e32 v19, v120, v50
	s_waitcnt vmcnt(46)
	v_pk_fma_f32 v[10:11], v[122:123], v[44:45], v[10:11] op_sel_hi:[0,1,1]
	v_pk_fma_f32 v[12:13], v[122:123], v[48:49], v[12:13] op_sel_hi:[0,1,1]
	v_fmac_f32_e32 v19, v122, v51
	s_waitcnt vmcnt(45)
	v_pk_fma_f32 v[10:11], v[124:125], v[36:37], v[10:11] op_sel_hi:[0,1,1]
	v_pk_fma_f32 v[12:13], v[124:125], v[46:47], v[12:13] op_sel_hi:[0,1,1]
	v_fmac_f32_e32 v19, v124, v58
	s_waitcnt vmcnt(44)
	v_pk_fma_f32 v[10:11], v[126:127], v[52:53], v[10:11] op_sel_hi:[0,1,1]
	v_pk_fma_f32 v[12:13], v[126:127], v[56:57], v[12:13] op_sel_hi:[0,1,1]
	v_fmac_f32_e32 v19, v126, v59
	s_waitcnt vmcnt(43)
	v_pk_fma_f32 v[10:11], v[128:129], v[38:39], v[10:11] op_sel_hi:[0,1,1]
	v_pk_fma_f32 v[12:13], v[128:129], v[54:55], v[12:13] op_sel_hi:[0,1,1]
	v_fmac_f32_e32 v19, v128, v66
	s_waitcnt vmcnt(42)
	v_pk_fma_f32 v[10:11], v[130:131], v[60:61], v[10:11] op_sel_hi:[0,1,1]
	v_pk_fma_f32 v[12:13], v[130:131], v[64:65], v[12:13] op_sel_hi:[0,1,1]
	v_fmac_f32_e32 v19, v130, v67
	s_waitcnt vmcnt(41)
	v_pk_fma_f32 v[10:11], v[132:133], v[40:41], v[10:11] op_sel_hi:[0,1,1]
	v_pk_fma_f32 v[12:13], v[132:133], v[62:63], v[12:13] op_sel_hi:[0,1,1]
	s_waitcnt lgkmcnt(0)
	v_fmac_f32_e32 v19, v132, v74
	s_waitcnt vmcnt(40)
	v_pk_fma_f32 v[10:11], v[134:135], v[68:69], v[10:11] op_sel_hi:[0,1,1]
	v_pk_fma_f32 v[12:13], v[134:135], v[72:73], v[12:13] op_sel_hi:[0,1,1]
	v_fmac_f32_e32 v19, v134, v75
	v_add_u32_e32 v23, 0x2000, v0
	ds_read2_b32 v[36:37], v0 offset1:2
	ds_read2_b32 v[38:39], v0 offset0:4 offset1:6
	ds_read2_b32 v[40:41], v0 offset0:8 offset1:10
	ds_read2_b32 v[42:43], v0 offset0:12 offset1:14
	v_add_u32_e32 v21, 0x1000, v0
	v_add_u32_e32 v25, 0x3000, v0
	v_add_u32_e32 v27, 0x4000, v0
	ds_read2_b32 v[44:45], v21 offset1:2
	ds_read2_b32 v[46:47], v23 offset1:2
	ds_read2_b32 v[48:49], v25 offset1:2
	ds_read2_b32 v[50:51], v27 offset1:2
	ds_read2_b32 v[52:53], v21 offset0:4 offset1:6
	ds_read2_b32 v[54:55], v23 offset0:4 offset1:6
	ds_read2_b32 v[56:57], v25 offset0:4 offset1:6
	ds_read2_b32 v[58:59], v27 offset0:4 offset1:6
	ds_read2_b32 v[60:61], v21 offset0:8 offset1:10
	ds_read2_b32 v[62:63], v23 offset0:8 offset1:10
	ds_read2_b32 v[64:65], v25 offset0:8 offset1:10
	ds_read2_b32 v[66:67], v27 offset0:8 offset1:10
	ds_read2_b32 v[68:69], v21 offset0:12 offset1:14
	ds_read2_b32 v[70:71], v23 offset0:12 offset1:14
	ds_read2_b32 v[72:73], v25 offset0:12 offset1:14
	ds_read2_b32 v[74:75], v27 offset0:12 offset1:14
	s_waitcnt lgkmcnt(14)
	v_mov_b32_e32 v76, v36
	v_mov_b32_e32 v77, v44
	v_mov_b32_e32 v78, v46
	s_waitcnt lgkmcnt(13)
	v_mov_b32_e32 v79, v48
	v_mov_b32_e32 v44, v37
	v_mov_b32_e32 v48, v47
	v_mov_b32_e32 v36, v38
	s_waitcnt lgkmcnt(11)
	v_mov_b32_e32 v37, v52
	s_waitcnt lgkmcnt(10)
	v_mov_b32_e32 v46, v54
	s_waitcnt lgkmcnt(9)
	v_mov_b32_e32 v47, v56
	v_mov_b32_e32 v52, v39
	v_mov_b32_e32 v56, v55
	v_mov_b32_e32 v38, v40
	s_waitcnt lgkmcnt(7)
	v_mov_b32_e32 v39, v60
	s_waitcnt lgkmcnt(6)
	v_mov_b32_e32 v54, v62
	s_waitcnt lgkmcnt(5)
	v_mov_b32_e32 v55, v64
	v_mov_b32_e32 v60, v41
	v_mov_b32_e32 v64, v63
	v_mov_b32_e32 v40, v42
	s_waitcnt lgkmcnt(3)
	v_mov_b32_e32 v41, v68
	s_waitcnt lgkmcnt(2)
	v_mov_b32_e32 v62, v70
	s_waitcnt lgkmcnt(1)
	v_mov_b32_e32 v63, v72
	v_mov_b32_e32 v68, v43
	v_mov_b32_e32 v72, v71
	v_add_u32_e32 v0, 64, v0
	s_waitcnt vmcnt(39)
	v_pk_fma_f32 v[10:11], v[136:137], v[76:77], v[10:11] op_sel_hi:[0,1,1]
	v_pk_fma_f32 v[12:13], v[136:137], v[78:79], v[12:13] op_sel_hi:[0,1,1]
	v_fmac_f32_e32 v19, v136, v50
	s_waitcnt vmcnt(38)
	v_pk_fma_f32 v[10:11], v[138:139], v[44:45], v[10:11] op_sel_hi:[0,1,1]
	v_pk_fma_f32 v[12:13], v[138:139], v[48:49], v[12:13] op_sel_hi:[0,1,1]
	v_fmac_f32_e32 v19, v138, v51
	s_waitcnt vmcnt(37)
	v_pk_fma_f32 v[10:11], v[140:141], v[36:37], v[10:11] op_sel_hi:[0,1,1]
	v_pk_fma_f32 v[12:13], v[140:141], v[46:47], v[12:13] op_sel_hi:[0,1,1]
	v_fmac_f32_e32 v19, v140, v58
	s_waitcnt vmcnt(36)
	v_pk_fma_f32 v[10:11], v[142:143], v[52:53], v[10:11] op_sel_hi:[0,1,1]
	v_pk_fma_f32 v[12:13], v[142:143], v[56:57], v[12:13] op_sel_hi:[0,1,1]
	v_fmac_f32_e32 v19, v142, v59
	s_waitcnt vmcnt(35)
	v_pk_fma_f32 v[10:11], v[144:145], v[38:39], v[10:11] op_sel_hi:[0,1,1]
	v_pk_fma_f32 v[12:13], v[144:145], v[54:55], v[12:13] op_sel_hi:[0,1,1]
	v_fmac_f32_e32 v19, v144, v66
	s_waitcnt vmcnt(34)
	v_pk_fma_f32 v[10:11], v[146:147], v[60:61], v[10:11] op_sel_hi:[0,1,1]
	v_pk_fma_f32 v[12:13], v[146:147], v[64:65], v[12:13] op_sel_hi:[0,1,1]
	v_fmac_f32_e32 v19, v146, v67
	s_waitcnt vmcnt(33)
	v_pk_fma_f32 v[10:11], v[148:149], v[40:41], v[10:11] op_sel_hi:[0,1,1]
	v_pk_fma_f32 v[12:13], v[148:149], v[62:63], v[12:13] op_sel_hi:[0,1,1]
	s_waitcnt lgkmcnt(0)
; __device__ __forceinline__ void mk_p0(const Ptrs& P, LAS unsigned char* lds, int tid, int wave, int lane, int bx, int G) {
;     ...
; #pragma unroll 8
;         for (int i = 0; i < 64; ++i) { const float wv = __builtin_nontemporal_load(wp + (size_t)(2 * i) * NMOD); const int k = 128 * wave + 2 * i + half;
; #pragma unroll
;             for (int r = 0; r < 5; ++r) acc[r] += sl[r * DM + k] * wv; }
	v_fmac_f32_e32 v19, v148, v74
	s_waitcnt vmcnt(32)
	v_pk_fma_f32 v[10:11], v[150:151], v[68:69], v[10:11] op_sel_hi:[0,1,1]
	v_pk_fma_f32 v[12:13], v[150:151], v[72:73], v[12:13] op_sel_hi:[0,1,1]
	v_fmac_f32_e32 v19, v150, v75
	v_add_u32_e32 v23, 0x2000, v0
	ds_read2_b32 v[36:37], v0 offset1:2
	ds_read2_b32 v[38:39], v0 offset0:4 offset1:6
	ds_read2_b32 v[40:41], v0 offset0:8 offset1:10
	ds_read2_b32 v[42:43], v0 offset0:12 offset1:14
	v_add_u32_e32 v21, 0x1000, v0
	v_add_u32_e32 v25, 0x3000, v0
	v_add_u32_e32 v27, 0x4000, v0
	ds_read2_b32 v[44:45], v21 offset1:2
	ds_read2_b32 v[46:47], v23 offset1:2
	ds_read2_b32 v[48:49], v25 offset1:2
	ds_read2_b32 v[50:51], v27 offset1:2
	ds_read2_b32 v[52:53], v21 offset0:4 offset1:6
	ds_read2_b32 v[54:55], v23 offset0:4 offset1:6
	ds_read2_b32 v[56:57], v25 offset0:4 offset1:6
	ds_read2_b32 v[58:59], v27 offset0:4 offset1:6
	ds_read2_b32 v[60:61], v21 offset0:8 offset1:10
	ds_read2_b32 v[62:63], v23 offset0:8 offset1:10
	ds_read2_b32 v[64:65], v25 offset0:8 offset1:10
	ds_read2_b32 v[66:67], v27 offset0:8 offset1:10
	ds_read2_b32 v[68:69], v21 offset0:12 offset1:14
	ds_read2_b32 v[70:71], v23 offset0:12 offset1:14
	ds_read2_b32 v[72:73], v25 offset0:12 offset1:14
	ds_read2_b32 v[74:75], v27 offset0:12 offset1:14
	s_waitcnt lgkmcnt(14)
	v_mov_b32_e32 v76, v36
	v_mov_b32_e32 v77, v44
	v_mov_b32_e32 v78, v46
	s_waitcnt lgkmcnt(13)
	v_mov_b32_e32 v79, v48
	v_mov_b32_e32 v44, v37
	v_mov_b32_e32 v48, v47
	v_mov_b32_e32 v36, v38
	s_waitcnt lgkmcnt(11)
	v_mov_b32_e32 v37, v52
	s_waitcnt lgkmcnt(10)
	v_mov_b32_e32 v46, v54
	s_waitcnt lgkmcnt(9)
	v_mov_b32_e32 v47, v56
	v_mov_b32_e32 v52, v39
	v_mov_b32_e32 v56, v55
	v_mov_b32_e32 v38, v40
	s_waitcnt lgkmcnt(7)
	v_mov_b32_e32 v39, v60
	s_waitcnt lgkmcnt(6)
	v_mov_b32_e32 v54, v62
	s_waitcnt lgkmcnt(5)
	v_mov_b32_e32 v55, v64
	v_mov_b32_e32 v60, v41
	v_mov_b32_e32 v64, v63
	v_mov_b32_e32 v40, v42
	s_waitcnt lgkmcnt(3)
	v_mov_b32_e32 v41, v68
	s_waitcnt lgkmcnt(2)
	v_mov_b32_e32 v62, v70
	s_waitcnt lgkmcnt(1)
	v_mov_b32_e32 v63, v72
	v_mov_b32_e32 v68, v43
	v_mov_b32_e32 v72, v71
	v_add_u32_e32 v0, 64, v0
	s_waitcnt vmcnt(31)
	v_pk_fma_f32 v[10:11], v[152:153], v[76:77], v[10:11] op_sel_hi:[0,1,1]
	v_pk_fma_f32 v[12:13], v[152:153], v[78:79], v[12:13] op_sel_hi:[0,1,1]
	v_fmac_f32_e32 v19, v152, v50
	s_waitcnt vmcnt(30)
	v_pk_fma_f32 v[10:11], v[154:155], v[44:45], v[10:11] op_sel_hi:[0,1,1]
	v_pk_fma_f32 v[12:13], v[154:155], v[48:49], v[12:13] op_sel_hi:[0,1,1]
	v_fmac_f32_e32 v19, v154, v51
	s_waitcnt vmcnt(29)
	v_pk_fma_f32 v[10:11], v[156:157], v[36:37], v[10:11] op_sel_hi:[0,1,1]
	v_pk_fma_f32 v[12:13], v[156:157], v[46:47], v[12:13] op_sel_hi:[0,1,1]
	v_fmac_f32_e32 v19, v156, v58
	s_waitcnt vmcnt(28)
	v_pk_fma_f32 v[10:11], v[158:159], v[52:53], v[10:11] op_sel_hi:[0,1,1]
	v_pk_fma_f32 v[12:13], v[158:159], v[56:57], v[12:13] op_sel_hi:[0,1,1]
	v_fmac_f32_e32 v19, v158, v59
	s_waitcnt vmcnt(27)
	v_pk_fma_f32 v[10:11], v[160:161], v[38:39], v[10:11] op_sel_hi:[0,1,1]
	v_pk_fma_f32 v[12:13], v[160:161], v[54:55], v[12:13] op_sel_hi:[0,1,1]
	v_fmac_f32_e32 v19, v160, v66
	s_waitcnt vmcnt(26)
	v_pk_fma_f32 v[10:11], v[162:163], v[60:61], v[10:11] op_sel_hi:[0,1,1]
	v_pk_fma_f32 v[12:13], v[162:163], v[64:65], v[12:13] op_sel_hi:[0,1,1]
	v_fmac_f32_e32 v19, v162, v67
	s_waitcnt vmcnt(25)
	v_pk_fma_f32 v[10:11], v[164:165], v[40:41], v[10:11] op_sel_hi:[0,1,1]
	v_pk_fma_f32 v[12:13], v[164:165], v[62:63], v[12:13] op_sel_hi:[0,1,1]
	s_waitcnt lgkmcnt(0)
	v_fmac_f32_e32 v19, v164, v74
	s_waitcnt vmcnt(24)
	v_pk_fma_f32 v[10:11], v[166:167], v[68:69], v[10:11] op_sel_hi:[0,1,1]
	v_pk_fma_f32 v[12:13], v[166:167], v[72:73], v[12:13] op_sel_hi:[0,1,1]
	v_fmac_f32_e32 v19, v166, v75
	v_add_u32_e32 v23, 0x2000, v0
	ds_read2_b32 v[36:37], v0 offset1:2
	ds_read2_b32 v[38:39], v0 offset0:4 offset1:6
	ds_read2_b32 v[40:41], v0 offset0:8 offset1:10
	ds_read2_b32 v[42:43], v0 offset0:12 offset1:14
	v_add_u32_e32 v21, 0x1000, v0
	v_add_u32_e32 v25, 0x3000, v0
	v_add_u32_e32 v27, 0x4000, v0
	ds_read2_b32 v[44:45], v21 offset1:2
	ds_read2_b32 v[46:47], v23 offset1:2
	ds_read2_b32 v[48:49], v25 offset1:2
	ds_read2_b32 v[50:51], v27 offset1:2
	ds_read2_b32 v[52:53], v21 offset0:4 offset1:6
	ds_read2_b32 v[54:55], v23 offset0:4 offset1:6
	ds_read2_b32 v[56:57], v25 offset0:4 offset1:6
	ds_read2_b32 v[58:59], v27 offset0:4 offset1:6
	ds_read2_b32 v[60:61], v21 offset0:8 offset1:10
	ds_read2_b32 v[62:63], v23 offset0:8 offset1:10
	ds_read2_b32 v[64:65], v25 offset0:8 offset1:10
	ds_read2_b32 v[66:67], v27 offset0:8 offset1:10
	ds_read2_b32 v[68:69], v21 offset0:12 offset1:14
	ds_read2_b32 v[70:71], v23 offset0:12 offset1:14
	ds_read2_b32 v[72:73], v25 offset0:12 offset1:14
	ds_read2_b32 v[74:75], v27 offset0:12 offset1:14
	s_waitcnt lgkmcnt(14)
	v_mov_b32_e32 v76, v36
	v_mov_b32_e32 v77, v44
	v_mov_b32_e32 v78, v46
	s_waitcnt lgkmcnt(13)
	v_mov_b32_e32 v79, v48
	v_mov_b32_e32 v44, v37
	v_mov_b32_e32 v48, v47
	v_mov_b32_e32 v36, v38
	s_waitcnt lgkmcnt(11)
	v_mov_b32_e32 v37, v52
	s_waitcnt lgkmcnt(10)
	v_mov_b32_e32 v46, v54
	s_waitcnt lgkmcnt(9)
	v_mov_b32_e32 v47, v56
	v_mov_b32_e32 v52, v39
	v_mov_b32_e32 v56, v55
	v_mov_b32_e32 v38, v40
	s_waitcnt lgkmcnt(7)
	v_mov_b32_e32 v39, v60
	s_waitcnt lgkmcnt(6)
	v_mov_b32_e32 v54, v62
	s_waitcnt lgkmcnt(5)
	v_mov_b32_e32 v55, v64
	v_mov_b32_e32 v60, v41
	v_mov_b32_e32 v64, v63
	v_mov_b32_e32 v40, v42
	s_waitcnt lgkmcnt(3)
	v_mov_b32_e32 v41, v68
	s_waitcnt lgkmcnt(2)
	v_mov_b32_e32 v62, v70
	s_waitcnt lgkmcnt(1)
	v_mov_b32_e32 v63, v72
	v_mov_b32_e32 v68, v43
	v_mov_b32_e32 v72, v71
	v_add_u32_e32 v0, 64, v0
	s_waitcnt vmcnt(23)
; __device__ __forceinline__ void mk_p0(const Ptrs& P, LAS unsigned char* lds, int tid, int wave, int lane, int bx, int G) {
;     ...
; #pragma unroll 8
;         for (int i = 0; i < 64; ++i) { const float wv = __builtin_nontemporal_load(wp + (size_t)(2 * i) * NMOD); const int k = 128 * wave + 2 * i + half;
; #pragma unroll
;             for (int r = 0; r < 5; ++r) acc[r] += sl[r * DM + k] * wv; }
	v_pk_fma_f32 v[10:11], v[168:169], v[76:77], v[10:11] op_sel_hi:[0,1,1]
	v_pk_fma_f32 v[12:13], v[168:169], v[78:79], v[12:13] op_sel_hi:[0,1,1]
	v_fmac_f32_e32 v19, v168, v50
	s_waitcnt vmcnt(22)
	v_pk_fma_f32 v[10:11], v[172:173], v[44:45], v[10:11] op_sel_hi:[0,1,1]
	v_pk_fma_f32 v[12:13], v[172:173], v[48:49], v[12:13] op_sel_hi:[0,1,1]
	v_fmac_f32_e32 v19, v172, v51
	s_waitcnt vmcnt(21)
	v_pk_fma_f32 v[10:11], v[174:175], v[36:37], v[10:11] op_sel_hi:[0,1,1]
	v_pk_fma_f32 v[12:13], v[174:175], v[46:47], v[12:13] op_sel_hi:[0,1,1]
	v_fmac_f32_e32 v19, v174, v58
	s_waitcnt vmcnt(20)
	v_pk_fma_f32 v[10:11], v[176:177], v[52:53], v[10:11] op_sel_hi:[0,1,1]
	v_pk_fma_f32 v[12:13], v[176:177], v[56:57], v[12:13] op_sel_hi:[0,1,1]
	v_fmac_f32_e32 v19, v176, v59
	s_waitcnt vmcnt(19)
	v_pk_fma_f32 v[10:11], v[178:179], v[38:39], v[10:11] op_sel_hi:[0,1,1]
	v_pk_fma_f32 v[12:13], v[178:179], v[54:55], v[12:13] op_sel_hi:[0,1,1]
	v_fmac_f32_e32 v19, v178, v66
	s_waitcnt vmcnt(18)
	v_pk_fma_f32 v[10:11], v[180:181], v[60:61], v[10:11] op_sel_hi:[0,1,1]
	v_pk_fma_f32 v[12:13], v[180:181], v[64:65], v[12:13] op_sel_hi:[0,1,1]
	v_fmac_f32_e32 v19, v180, v67
	s_waitcnt vmcnt(17)
	v_pk_fma_f32 v[10:11], v[182:183], v[40:41], v[10:11] op_sel_hi:[0,1,1]
	v_pk_fma_f32 v[12:13], v[182:183], v[62:63], v[12:13] op_sel_hi:[0,1,1]
	s_waitcnt lgkmcnt(0)
	v_fmac_f32_e32 v19, v182, v74
	s_waitcnt vmcnt(16)
	v_pk_fma_f32 v[10:11], v[184:185], v[68:69], v[10:11] op_sel_hi:[0,1,1]
	v_pk_fma_f32 v[12:13], v[184:185], v[72:73], v[12:13] op_sel_hi:[0,1,1]
	v_fmac_f32_e32 v19, v184, v75
	v_add_u32_e32 v23, 0x2000, v0
	ds_read2_b32 v[36:37], v0 offset1:2
	ds_read2_b32 v[38:39], v0 offset0:4 offset1:6
	ds_read2_b32 v[40:41], v0 offset0:8 offset1:10
	ds_read2_b32 v[42:43], v0 offset0:12 offset1:14
	v_add_u32_e32 v21, 0x1000, v0
	v_add_u32_e32 v25, 0x3000, v0
	v_add_u32_e32 v27, 0x4000, v0
	ds_read2_b32 v[44:45], v21 offset1:2
	ds_read2_b32 v[46:47], v23 offset1:2
	ds_read2_b32 v[48:49], v25 offset1:2
	ds_read2_b32 v[50:51], v27 offset1:2
	ds_read2_b32 v[52:53], v21 offset0:4 offset1:6
	ds_read2_b32 v[54:55], v23 offset0:4 offset1:6
	ds_read2_b32 v[56:57], v25 offset0:4 offset1:6
	ds_read2_b32 v[58:59], v27 offset0:4 offset1:6
	ds_read2_b32 v[60:61], v21 offset0:8 offset1:10
	ds_read2_b32 v[62:63], v23 offset0:8 offset1:10
	ds_read2_b32 v[64:65], v25 offset0:8 offset1:10
	ds_read2_b32 v[66:67], v27 offset0:8 offset1:10
	ds_read2_b32 v[68:69], v21 offset0:12 offset1:14
	ds_read2_b32 v[70:71], v23 offset0:12 offset1:14
	ds_read2_b32 v[72:73], v25 offset0:12 offset1:14
	ds_read2_b32 v[74:75], v27 offset0:12 offset1:14
	s_waitcnt lgkmcnt(14)
	v_mov_b32_e32 v76, v36
	v_mov_b32_e32 v77, v44
	v_mov_b32_e32 v78, v46
	s_waitcnt lgkmcnt(13)
	v_mov_b32_e32 v79, v48
	v_mov_b32_e32 v44, v37
	v_mov_b32_e32 v48, v47
	v_mov_b32_e32 v36, v38
	s_waitcnt lgkmcnt(11)
	v_mov_b32_e32 v37, v52
	s_waitcnt lgkmcnt(10)
	v_mov_b32_e32 v46, v54
	s_waitcnt lgkmcnt(9)
	v_mov_b32_e32 v47, v56
	v_mov_b32_e32 v52, v39
	v_mov_b32_e32 v56, v55
	v_mov_b32_e32 v38, v40
	s_waitcnt lgkmcnt(7)
	v_mov_b32_e32 v39, v60
	s_waitcnt lgkmcnt(6)
	v_mov_b32_e32 v54, v62
	s_waitcnt lgkmcnt(5)
	v_mov_b32_e32 v55, v64
	v_mov_b32_e32 v60, v41
	v_mov_b32_e32 v64, v63
	v_mov_b32_e32 v40, v42
	s_waitcnt lgkmcnt(3)
	v_mov_b32_e32 v41, v68
	s_waitcnt lgkmcnt(2)
	v_mov_b32_e32 v62, v70
	s_waitcnt lgkmcnt(1)
	v_mov_b32_e32 v63, v72
	v_mov_b32_e32 v68, v43
	v_mov_b32_e32 v72, v71
	v_add_u32_e32 v0, 64, v0
	s_waitcnt vmcnt(15)
	v_pk_fma_f32 v[10:11], v[186:187], v[76:77], v[10:11] op_sel_hi:[0,1,1]
	v_pk_fma_f32 v[12:13], v[186:187], v[78:79], v[12:13] op_sel_hi:[0,1,1]
	v_fmac_f32_e32 v19, v186, v50
	s_waitcnt vmcnt(14)
	v_pk_fma_f32 v[10:11], v[188:189], v[44:45], v[10:11] op_sel_hi:[0,1,1]
	v_pk_fma_f32 v[12:13], v[188:189], v[48:49], v[12:13] op_sel_hi:[0,1,1]
	v_fmac_f32_e32 v19, v188, v51
	s_waitcnt vmcnt(13)
	v_pk_fma_f32 v[10:11], v[190:191], v[36:37], v[10:11] op_sel_hi:[0,1,1]
	v_pk_fma_f32 v[12:13], v[190:191], v[46:47], v[12:13] op_sel_hi:[0,1,1]
	v_fmac_f32_e32 v19, v190, v58
	s_waitcnt vmcnt(12)
	v_pk_fma_f32 v[10:11], v[192:193], v[52:53], v[10:11] op_sel_hi:[0,1,1]
	v_pk_fma_f32 v[12:13], v[192:193], v[56:57], v[12:13] op_sel_hi:[0,1,1]
	v_fmac_f32_e32 v19, v192, v59
	s_waitcnt vmcnt(11)
	v_pk_fma_f32 v[10:11], v[194:195], v[38:39], v[10:11] op_sel_hi:[0,1,1]
	v_pk_fma_f32 v[12:13], v[194:195], v[54:55], v[12:13] op_sel_hi:[0,1,1]
	v_fmac_f32_e32 v19, v194, v66
	s_waitcnt vmcnt(10)
	v_pk_fma_f32 v[10:11], v[196:197], v[60:61], v[10:11] op_sel_hi:[0,1,1]
	v_pk_fma_f32 v[12:13], v[196:197], v[64:65], v[12:13] op_sel_hi:[0,1,1]
	v_fmac_f32_e32 v19, v196, v67
	s_waitcnt vmcnt(9)
	v_pk_fma_f32 v[10:11], v[198:199], v[40:41], v[10:11] op_sel_hi:[0,1,1]
	v_pk_fma_f32 v[12:13], v[198:199], v[62:63], v[12:13] op_sel_hi:[0,1,1]
	s_waitcnt lgkmcnt(0)
	v_fmac_f32_e32 v19, v198, v74
	s_waitcnt vmcnt(8)
; __device__ __forceinline__ void mk_p0(const Ptrs& P, LAS unsigned char* lds, int tid, int wave, int lane, int bx, int G) {
;     ...
; #pragma unroll 8
;         for (int i = 0; i < 64; ++i) { const float wv = __builtin_nontemporal_load(wp + (size_t)(2 * i) * NMOD); const int k = 128 * wave + 2 * i + half;
; #pragma unroll
;             for (int r = 0; r < 5; ++r) acc[r] += sl[r * DM + k] * wv; }
; #pragma unroll
;         for (int r = 0; r < 5; ++r) red[((wave * 2 + half) * 5 + r) * 32 + col] = acc[r];
;         __syncthreads();
;         if (tid < 160) { const int r = tid >> 5, c = tid & 31; float s = 0.f;
; #pragma unroll
;             for (int p = 0; p < 16; ++p) s += red[(p * 5 + r) * 32 + c];
;             ((float*)(ws + WS_MOD))[(size_t)r * NMOD + 32 * cgp + c] = s + P.mod_b[32 * cgp + c]; }
	v_pk_fma_f32 v[10:11], v[200:201], v[68:69], v[10:11] op_sel_hi:[0,1,1]
	v_pk_fma_f32 v[12:13], v[200:201], v[72:73], v[12:13] op_sel_hi:[0,1,1]
	v_fmac_f32_e32 v19, v200, v75
	v_add_u32_e32 v23, 0x2000, v0
	ds_read2_b32 v[36:37], v0 offset1:2
	ds_read2_b32 v[38:39], v0 offset0:4 offset1:6
	ds_read2_b32 v[40:41], v0 offset0:8 offset1:10
	ds_read2_b32 v[42:43], v0 offset0:12 offset1:14
	v_add_u32_e32 v21, 0x1000, v0
	v_add_u32_e32 v25, 0x3000, v0
	v_add_u32_e32 v27, 0x4000, v0
	ds_read2_b32 v[44:45], v21 offset1:2
	ds_read2_b32 v[46:47], v23 offset1:2
	ds_read2_b32 v[48:49], v25 offset1:2
	ds_read2_b32 v[50:51], v27 offset1:2
	ds_read2_b32 v[52:53], v21 offset0:4 offset1:6
	ds_read2_b32 v[54:55], v23 offset0:4 offset1:6
	ds_read2_b32 v[56:57], v25 offset0:4 offset1:6
	ds_read2_b32 v[58:59], v27 offset0:4 offset1:6
	ds_read2_b32 v[60:61], v21 offset0:8 offset1:10
	ds_read2_b32 v[62:63], v23 offset0:8 offset1:10
	ds_read2_b32 v[64:65], v25 offset0:8 offset1:10
	ds_read2_b32 v[66:67], v27 offset0:8 offset1:10
	ds_read2_b32 v[68:69], v21 offset0:12 offset1:14
	ds_read2_b32 v[70:71], v23 offset0:12 offset1:14
	ds_read2_b32 v[72:73], v25 offset0:12 offset1:14
	ds_read2_b32 v[74:75], v27 offset0:12 offset1:14
	s_waitcnt lgkmcnt(14)
	v_mov_b32_e32 v76, v36
	v_mov_b32_e32 v77, v44
	v_mov_b32_e32 v78, v46
	s_waitcnt lgkmcnt(13)
	v_mov_b32_e32 v79, v48
	v_mov_b32_e32 v44, v37
	v_mov_b32_e32 v48, v47
	v_mov_b32_e32 v36, v38
	s_waitcnt lgkmcnt(11)
	v_mov_b32_e32 v37, v52
	s_waitcnt lgkmcnt(10)
	v_mov_b32_e32 v46, v54
	s_waitcnt lgkmcnt(9)
	v_mov_b32_e32 v47, v56
	v_mov_b32_e32 v52, v39
	v_mov_b32_e32 v56, v55
	v_mov_b32_e32 v38, v40
	s_waitcnt lgkmcnt(7)
	v_mov_b32_e32 v39, v60
	s_waitcnt lgkmcnt(6)
	v_mov_b32_e32 v54, v62
	s_waitcnt lgkmcnt(5)
	v_mov_b32_e32 v55, v64
	v_mov_b32_e32 v60, v41
	v_mov_b32_e32 v64, v63
	v_mov_b32_e32 v40, v42
	s_waitcnt lgkmcnt(3)
	v_mov_b32_e32 v41, v68
	s_waitcnt lgkmcnt(2)
	v_mov_b32_e32 v62, v70
	s_waitcnt lgkmcnt(1)
	v_mov_b32_e32 v63, v72
	v_mov_b32_e32 v68, v43
	v_mov_b32_e32 v72, v71
	v_add_u32_e32 v0, 64, v0
	s_waitcnt vmcnt(7)
	v_pk_fma_f32 v[10:11], v[202:203], v[76:77], v[10:11] op_sel_hi:[0,1,1]
	v_pk_fma_f32 v[12:13], v[202:203], v[78:79], v[12:13] op_sel_hi:[0,1,1]
	v_fmac_f32_e32 v19, v202, v50
	s_waitcnt vmcnt(6)
	v_pk_fma_f32 v[10:11], v[204:205], v[44:45], v[10:11] op_sel_hi:[0,1,1]
	v_pk_fma_f32 v[12:13], v[204:205], v[48:49], v[12:13] op_sel_hi:[0,1,1]
	v_fmac_f32_e32 v19, v204, v51
	s_waitcnt vmcnt(5)
	v_pk_fma_f32 v[10:11], v[206:207], v[36:37], v[10:11] op_sel_hi:[0,1,1]
	v_pk_fma_f32 v[12:13], v[206:207], v[46:47], v[12:13] op_sel_hi:[0,1,1]
	v_fmac_f32_e32 v19, v206, v58
	s_waitcnt vmcnt(4)
	v_pk_fma_f32 v[10:11], v[210:211], v[52:53], v[10:11] op_sel_hi:[0,1,1]
	v_pk_fma_f32 v[12:13], v[210:211], v[56:57], v[12:13] op_sel_hi:[0,1,1]
	v_fmac_f32_e32 v19, v210, v59
	s_waitcnt vmcnt(3)
	v_pk_fma_f32 v[10:11], v[212:213], v[38:39], v[10:11] op_sel_hi:[0,1,1]
	v_pk_fma_f32 v[12:13], v[212:213], v[54:55], v[12:13] op_sel_hi:[0,1,1]
	v_fmac_f32_e32 v19, v212, v66
	s_waitcnt vmcnt(2)
	v_pk_fma_f32 v[10:11], v[214:215], v[60:61], v[10:11] op_sel_hi:[0,1,1]
	v_pk_fma_f32 v[12:13], v[214:215], v[64:65], v[12:13] op_sel_hi:[0,1,1]
	v_fmac_f32_e32 v19, v214, v67
	s_waitcnt vmcnt(1)
	v_pk_fma_f32 v[10:11], v[216:217], v[40:41], v[10:11] op_sel_hi:[0,1,1]
	v_pk_fma_f32 v[12:13], v[216:217], v[62:63], v[12:13] op_sel_hi:[0,1,1]
	s_waitcnt lgkmcnt(0)
	v_fmac_f32_e32 v19, v216, v74
	s_waitcnt vmcnt(0)
	v_pk_fma_f32 v[10:11], v[220:221], v[68:69], v[10:11] op_sel_hi:[0,1,1]
	v_pk_fma_f32 v[12:13], v[220:221], v[72:73], v[12:13] op_sel_hi:[0,1,1]
	v_fmac_f32_e32 v19, v220, v75
	v_add_u32_e32 v0, 0x8000, v17
	ds_write2_b32 v0, v10, v11 offset1:32
	ds_write2_b32 v0, v12, v13 offset0:64 offset1:96
	ds_write_b32 v17, v19 offset:33280
	s_waitcnt lgkmcnt(0)
	s_barrier
	s_and_saveexec_b64 s[0:1], vcc
	s_cbranch_execz .LBB9_73
	s_lshl_b32 s2, s28, 5
	v_or_b32_e32 v8, s2, v14
	v_readlane_b32 s44, v251, 0
	v_ashrrev_i32_e32 v9, 31, v8
	v_readlane_b32 s54, v251, 10
	v_readlane_b32 s55, v251, 11
	v_add_u32_e32 v10, 0x8400, v18
	v_add_u32_e32 v12, 0x8a00, v18
	v_lshl_add_u64 v[8:9], v[8:9], 2, s[54:55]
	global_load_dword v0, v[8:9], off
	v_add_u32_e32 v8, 0x8000, v18
	v_add_u32_e32 v22, 0x9400, v18
	v_add_u32_e32 v24, 0x9800, v18
	v_add_u32_e32 v26, 0x9e00, v18
	v_add_u32_e32 v28, 0xa200, v18
	v_add_u32_e32 v19, 0x8e00, v18
	ds_read2_b32 v[8:9], v8 offset1:160
	ds_read2_b32 v[10:11], v10 offset0:64 offset1:224
	ds_read2_b32 v[12:13], v12 offset1:160
	ds_read2_b32 v[20:21], v19 offset0:64 offset1:224
	ds_read2_b32 v[22:23], v22 offset1:160
	ds_read2_b32 v[24:25], v24 offset0:64 offset1:224
	ds_read2_b32 v[26:27], v26 offset1:160
	ds_read2_b32 v[28:29], v28 offset0:64 offset1:224
	s_waitcnt lgkmcnt(7)
	v_add_f32_e32 v8, 0, v8
	v_add_f32_e32 v8, v8, v9
	s_waitcnt lgkmcnt(6)
	v_add_f32_e32 v8, v8, v10
	v_add_f32_e32 v8, v8, v11
	s_waitcnt lgkmcnt(5)
	v_add_f32_e32 v8, v8, v12
	v_add_f32_e32 v8, v8, v13
	s_waitcnt lgkmcnt(4)
	v_add_f32_e32 v8, v8, v20
	v_add_f32_e32 v8, v8, v21
	s_waitcnt lgkmcnt(3)
	v_add_f32_e32 v8, v8, v22
	v_add_f32_e32 v8, v8, v23
	s_waitcnt lgkmcnt(2)
	v_add_f32_e32 v8, v8, v24
	v_add_f32_e32 v8, v8, v25
	s_waitcnt lgkmcnt(1)
	v_add_f32_e32 v8, v8, v26
	v_add_f32_e32 v8, v8, v27
	s_waitcnt lgkmcnt(0)
	v_add_f32_e32 v8, v8, v28
	s_ashr_i32 s3, s2, 31
	v_add_f32_e32 v8, v8, v29
	v_readlane_b32 s45, v251, 1
	v_readlane_b32 s46, v251, 2
	v_readlane_b32 s47, v251, 3
	v_readlane_b32 s48, v251, 4
	v_readlane_b32 s49, v251, 5
	v_readlane_b32 s50, v251, 6
	v_readlane_b32 s51, v251, 7
	v_readlane_b32 s52, v251, 8
	v_readlane_b32 s53, v251, 9
	v_readlane_b32 s56, v251, 12
	v_readlane_b32 s57, v251, 13
	v_readlane_b32 s58, v251, 14
	v_readlane_b32 s59, v251, 15
	s_waitcnt vmcnt(0)
	v_add_f32_e32 v0, v8, v0
	v_lshl_add_u64 v[8:9], s[2:3], 2, v[2:3]
	global_store_dword v[8:9], v0, off
	s_branch .LBB9_73
